# v056 + cross-attention prompt loop tile-issue blocks: m0 save/restore around each LDS-DMA piece removed (SALU trimming)
# speedup vs baseline: 1.0040x; 1.0040x over previous
; #define LAS __attribute__((address_space(3)))
; DI unsigned lds_addr(const LAS void* p) { return (unsigned)__builtin_amdgcn_readfirstlane((int)(unsigned)(size_t)p); }
; DI void load_tile(LAS unsigned char* buf, const bf16* Kg, const bf16* Vg, int kv0, int wave, int lane) {
; #pragma unroll
;     for (int i = 0; i < 2; ++i) { const int pc = 2 * wave + i;
;         glds16(Kg + (size_t)(kv0 + (lane & 31)) * 2048 + (2 * pc + (lane >> 5)) * 8, lds_addr(buf + pc * 1024)); }
; #pragma unroll
;     for (int i = 0; i < 2; ++i) { const int pc = 2 * wave + i;
;         glds16(Vg + (size_t)(kv0 + 16 * (pc & 1) + (lane >> 2)) * 2048 + (pc >> 1) * 32 + (lane & 3) * 8, lds_addr(buf + KT + (pc >> 1) * 2048 + (pc & 1) * 1024)); }
; }
; DI void cross_unit(Ctx A_, LAS unsigned char* lds, int kvb, int hc, size_t row0, int nrows, int wave, int lane) {
;     ...
;         asm volatile("s_waitcnt vmcnt(0) lgkmcnt(0)" ::: "memory"); __builtin_amdgcn_s_barrier(); asm volatile("" ::: "memory");
;         if (t + 1 < 8) load_tile(lds + ((t + 1) & 1) * BUF, Kg, Vg, (t + 1) * 32, wave, lane);
.Lc3_w1:
	s_barrier
	s_cmp_eq_u32 s2, 0x38000
	s_cbranch_scc1 .Lcross_touch_s
	s_cmp_eq_u32 s2, 0x30000
	s_cbranch_scc1 .LBB0_928
	s_mov_b32 s34, s98
	v_lshl_add_u64 v[4:5], v[168:169], 1, v[166:167]
	s_add_i32 s35, s34, s33
	s_mov_b32 m0, s35
	s_nop 0
	global_load_lds_dwordx4 v[4:5], off
	v_lshl_add_u64 v[4:5], v[170:171], 1, v[166:167]
	s_add_i32 s34, s34, s38
	s_mov_b32 m0, s34
	s_nop 0
	global_load_lds_dwordx4 v[4:5], off
	s_add_i32 s34, s35, 0x4000
	s_mov_b32 m0, s34
	s_nop 0
	global_load_lds_dwordx4 v[172:173], off
	v_lshl_add_u64 v[4:5], v[172:173], 0, s[20:21]
	s_add_i32 s34, s35, 0x4400
	s_mov_b32 m0, s34
	s_nop 0
	global_load_lds_dwordx4 v[4:5], off
	s_add_i32 s98, s98, 0x8000
	s_cmp_eq_u32 s98, 0x18000
	s_cselect_b32 s98, 0, s98
	s_branch .LBB0_928
